# adds phase 4 (layer-0 mixer norm): the four bf16 delta loads of a row issued together with its input loads
# speedup vs baseline: 1.0112x; 1.0018x over previous
; #define GAS __attribute__((address_space(1)))
; __device__ __forceinline__ void f32_load8_nt(const float* row, int lane, float (&v)[4][8]) {
; #pragma unroll
;     for (int j = 0; j < 4; ++j) { const GAS f32x4* p = (const GAS f32x4*)(row + 8 * (lane + 64 * j)); const f32x4 a = __builtin_nontemporal_load(p), b = __builtin_nontemporal_load(p + 1);
; #pragma unroll
;         for (int q = 0; q < 4; ++q) { v[j][q] = a[q]; v[j][4 + q] = b[q]; } }
; }
; __device__ __forceinline__ void bf16_add8(const bf16* row, int lane, float (&v)[4][8]) {
; #pragma unroll
;     for (int j = 0; j < 4; ++j) { const v4u d = __builtin_nontemporal_load((const GAS v4u*)(row + 8 * (lane + 64 * j)));
; #pragma unroll
;         for (int q = 0; q < 4; ++q) { v[j][2 * q] += bf2f(d[q] & 0xffffu); v[j][2 * q + 1] += bf2f(d[q] >> 16); } }
; }
; __device__ __forceinline__ void norm_phase(bool from_input, int gw, int NGW, int lane_in, float* H, const float* x_in, const float* c_in, const float* gain, const float* modL, int js, int jc, bf16* XN, ...
;     ...
;         if (from_input || (pend && s_from_input)) f32_load8_nt(s < 256 ? c_in + ((size_t)b * 256 + s) * 2048 : x_in + ((size_t)b * 8192 + (s - 256)) * 2048, lane, v);
;         else h24_load(Hb, (size_t)r, lane, v);
;         if (DLT && s >= 256) { bf16_add8(DLT + (size_t)r * 2048, lane, v); h24_store(Hb, (size_t)r, lane, v); }
.LBB0_484:
	s_lshl_b64 s[4:5], s[36:37], 13
	s_add_u32 s4, s12, s4
	s_addc_u32 s5, s13, s5
	v_lshl_add_u64 v[32:33], s[4:5], 0, v[74:75]
	global_load_dwordx4 v[56:59], v74, s[4:5] offset:16 nt
	global_load_dwordx4 v[60:63], v74, s[4:5] nt
	global_load_dwordx4 v[48:51], v74, s[4:5] offset:2064 nt
	global_load_dwordx4 v[52:55], v74, s[4:5] offset:2048 nt
	s_mov_b64 s[4:5], 0x1000
	v_lshl_add_u64 v[34:35], v[32:33], 0, s[4:5]
	s_movk_i32 s4, 0x1000
	v_add_co_u32_e32 v36, vcc, s4, v32
	s_mov_b64 s[4:5], 0x1800
	s_nop 0
	v_addc_co_u32_e32 v37, vcc, 0, v33, vcc
	v_lshl_add_u64 v[32:33], v[32:33], 0, s[4:5]
	global_load_dwordx4 v[44:47], v[36:37], off nt
	global_load_dwordx4 v[40:43], v[34:35], off offset:16 nt
	s_nop 0
	global_load_dwordx4 v[36:39], v[36:37], off offset:2048 nt
	s_nop 0
	global_load_dwordx4 v[32:35], v[32:33], off offset:16 nt
	v_lshlrev_b64 v[204:205], 12, s[34:35]
	v_lshl_add_u64 v[204:205], v[204:205], 0, v[82:83]
	global_load_dwordx4 v[188:191], v[204:205], off nt
	global_load_dwordx4 v[192:195], v[204:205], off offset:1024 nt
	global_load_dwordx4 v[196:199], v[204:205], off offset:2048 nt
	global_load_dwordx4 v[200:203], v[204:205], off offset:3072 nt
	s_cmpk_lt_u32 s44, 0x100
	s_cbranch_scc1 .LBB0_486
	s_lshl_b64 s[4:5], s[34:35], 12
	v_lshl_add_u64 v[68:69], v[82:83], 0, s[4:5]
	s_lshl_b64 s[36:37], s[34:35], 11
	s_waitcnt vmcnt(3)
	v_lshlrev_b32_e32 v70, 16, v188
	v_and_b32_e32 v71, 0xffff0000, v188
	v_lshlrev_b32_e32 v64, 16, v189
	v_and_b32_e32 v65, 0xffff0000, v189
	v_pk_add_f32 v[62:63], v[62:63], v[64:65]
	v_lshlrev_b32_e32 v64, 16, v190
	v_and_b32_e32 v65, 0xffff0000, v190
	v_pk_add_f32 v[56:57], v[56:57], v[64:65]
	v_lshlrev_b32_e32 v64, 16, v191
	v_and_b32_e32 v65, 0xffff0000, v191
	v_pk_add_f32 v[58:59], v[58:59], v[64:65]
	v_pk_add_f32 v[60:61], v[60:61], v[70:71]
	v_add_u32_e32 v74, 0x800, v56
	v_add_u32_e32 v79, 0x800, v58
	v_add_u32_e32 v142, 0x800, v57
	v_add_u32_e32 v81, 0x800, v59
	s_waitcnt vmcnt(2)
	v_lshlrev_b32_e32 v70, 16, v192
	v_and_b32_e32 v71, 0xffff0000, v192
	v_lshlrev_b32_e32 v64, 16, v193
	v_and_b32_e32 v65, 0xffff0000, v193
	v_pk_add_f32 v[54:55], v[54:55], v[64:65]
	v_lshlrev_b32_e32 v64, 16, v194
	v_and_b32_e32 v65, 0xffff0000, v194
	v_pk_add_f32 v[48:49], v[48:49], v[64:65]
	v_lshlrev_b32_e32 v64, 16, v195
	v_and_b32_e32 v65, 0xffff0000, v195
	v_pk_add_f32 v[50:51], v[50:51], v[64:65]
	v_pk_add_f32 v[52:53], v[52:53], v[70:71]
	s_waitcnt vmcnt(1)
	v_lshlrev_b32_e32 v70, 16, v196
	v_and_b32_e32 v71, 0xffff0000, v196
	v_lshlrev_b32_e32 v64, 16, v197
	v_and_b32_e32 v65, 0xffff0000, v197
	v_pk_add_f32 v[46:47], v[46:47], v[64:65]
	v_lshlrev_b32_e32 v64, 16, v198
	v_and_b32_e32 v65, 0xffff0000, v198
	v_pk_add_f32 v[40:41], v[40:41], v[64:65]
	v_lshlrev_b32_e32 v64, 16, v199
	v_and_b32_e32 v65, 0xffff0000, v199
	v_pk_add_f32 v[42:43], v[42:43], v[64:65]
	v_pk_add_f32 v[44:45], v[44:45], v[70:71]
	v_add_u32_e32 v70, 0x800, v63
	v_add_u32_e32 v71, 0x800, v61
	s_waitcnt vmcnt(0)
; #define GAS __attribute__((address_space(1)))
; __device__ __forceinline__ void h24_store(unsigned char* Hb, size_t r, int lane, const float (&v)[4][8]) {
; #pragma unroll
;     for (int j = 0; j < 4; ++j) { const size_t e = r * 2048 + 8 * (lane + 64 * j); unsigned u[8];
; #pragma unroll
;         for (int q = 0; q < 8; ++q) u[q] = __builtin_bit_cast(unsigned, v[j][q]) + 0x800u;
;         v4u hi; unsigned lo = 0u;
; #pragma unroll
;         for (int q = 0; q < 4; ++q) hi[q] = (u[2 * q] >> 16) | (u[2 * q + 1] & 0xffff0000u);
; #pragma unroll
;         for (int q = 0; q < 8; ++q) lo |= ((u[q] >> 12) & 0xfu) << (4 * q);
;         __builtin_nontemporal_store(hi, (GAS v4u*)(Hb + e * 2)); __builtin_nontemporal_store(lo, (GAS unsigned*)(Hb + H_LO_OFF + (e >> 1))); }
; }
; __device__ __forceinline__ void f32_load8(const float* row, int lane, float (&v)[4][8]) {
; #pragma unroll
;     for (int j = 0; j < 4; ++j) { const GAS f32x4* p = (const GAS f32x4*)(row + 8 * (lane + 64 * j)); const f32x4 a = p[0], b = p[1];
; #pragma unroll
;         for (int q = 0; q < 4; ++q) { v[j][q] = a[q]; v[j][4 + q] = b[q]; } }
; }
; __device__ __forceinline__ void f32_load8_nt(const float* row, int lane, float (&v)[4][8]) {
; #pragma unroll
;     for (int j = 0; j < 4; ++j) { const GAS f32x4* p = (const GAS f32x4*)(row + 8 * (lane + 64 * j)); const f32x4 a = __builtin_nontemporal_load(p), b = __builtin_nontemporal_load(p + 1);
; #pragma unroll
;         for (int q = 0; q < 4; ++q) { v[j][q] = a[q]; v[j][4 + q] = b[q]; } }
; }
; __device__ __forceinline__ void bf16_add8(const bf16* row, int lane, float (&v)[4][8]) {
; #pragma unroll
;     for (int j = 0; j < 4; ++j) { const v4u d = __builtin_nontemporal_load((const GAS v4u*)(row + 8 * (lane + 64 * j)));
; #pragma unroll
;         for (int q = 0; q < 4; ++q) { v[j][2 * q] += bf2f(d[q] & 0xffffu); v[j][2 * q + 1] += bf2f(d[q] >> 16); } }
; }
	v_lshlrev_b32_e32 v68, 16, v200
	v_and_b32_e32 v69, 0xffff0000, v200
	v_lshlrev_b32_e32 v64, 16, v201
	v_and_b32_e32 v65, 0xffff0000, v201
	v_pk_add_f32 v[38:39], v[38:39], v[64:65]
	v_lshlrev_b32_e32 v64, 16, v202
	v_and_b32_e32 v65, 0xffff0000, v202
	v_pk_add_f32 v[36:37], v[36:37], v[68:69]
	v_pk_add_f32 v[32:33], v[32:33], v[64:65]
	v_lshlrev_b32_e32 v64, 16, v203
	v_and_b32_e32 v65, 0xffff0000, v203
	v_add_u32_e32 v68, 0x800, v60
	v_add_u32_e32 v69, 0x800, v62
	v_pk_add_f32 v[34:35], v[34:35], v[64:65]
	v_lshrrev_b32_e32 v65, 16, v69
	v_lshrrev_b32_e32 v64, 16, v68
	v_lshrrev_b32_e32 v66, 16, v74
	v_and_or_b32 v64, v71, s3, v64
	v_and_or_b32 v65, v70, s3, v65
	v_lshrrev_b32_e32 v68, 12, v68
	v_lshrrev_b32_e32 v71, 8, v71
	v_lshrrev_b32_e32 v69, 4, v69
	v_and_b32_e32 v70, 0xf000, v70
	v_lshrrev_b32_e32 v67, 16, v79
	v_and_or_b32 v66, v142, s3, v66
	v_and_b32_e32 v71, 0xf0, v71
	v_and_b32_e32 v69, 0xf00, v69
	v_lshlrev_b32_e32 v74, 4, v74
	v_lshlrev_b32_e32 v142, 8, v142
	v_and_or_b32 v68, v68, 15, v70
	v_and_or_b32 v67, v81, s3, v67
	v_and_b32_e32 v74, 0xf0000, v74
	v_and_b32_e32 v142, 0xf00000, v142
	v_lshlrev_b32_e32 v79, 12, v79
	v_lshlrev_b32_e32 v81, 16, v81
	v_or3_b32 v68, v68, v71, v69
	v_and_b32_e32 v79, 0xf000000, v79
	v_and_b32_e32 v81, 0xf0000000, v81
	v_or3_b32 v68, v68, v74, v142
	v_or3_b32 v74, v68, v79, v81
	v_mov_b32_e32 v69, s37
	v_or_b32_e32 v68, s36, v72
	v_lshl_add_u64 v[70:71], v[68:69], 1, s[90:91]
	global_store_dwordx4 v[70:71], v[64:67], off nt
	v_add_u32_e32 v70, 0x800, v55
	v_add_u32_e32 v71, 0x800, v53
	v_lshrrev_b64 v[64:65], 1, v[68:69]
	v_lshl_add_u64 v[64:65], s[78:79], 0, v[64:65]
	v_add_u32_e32 v68, 0x800, v52
	v_add_u32_e32 v69, 0x800, v54
	global_store_dword v[64:65], v74, off nt
	v_add_u32_e32 v74, 0x800, v48
	v_lshrrev_b32_e32 v65, 16, v69
	v_lshrrev_b32_e32 v64, 16, v68
	v_add_u32_e32 v79, 0x800, v50
	v_add_u32_e32 v142, 0x800, v49
	v_lshrrev_b32_e32 v66, 16, v74
	v_and_or_b32 v64, v71, s3, v64
	v_and_or_b32 v65, v70, s3, v65
	v_lshrrev_b32_e32 v68, 12, v68
	v_lshrrev_b32_e32 v71, 8, v71
	v_lshrrev_b32_e32 v69, 4, v69
	v_and_b32_e32 v70, 0xf000, v70
	v_add_u32_e32 v81, 0x800, v51
	v_lshrrev_b32_e32 v67, 16, v79
	v_and_or_b32 v66, v142, s3, v66
	v_and_b32_e32 v71, 0xf0, v71
	v_and_b32_e32 v69, 0xf00, v69
	v_lshlrev_b32_e32 v74, 4, v74
	v_lshlrev_b32_e32 v142, 8, v142
	v_and_or_b32 v68, v68, 15, v70
	v_and_or_b32 v67, v81, s3, v67
	v_and_b32_e32 v74, 0xf0000, v74
	v_and_b32_e32 v142, 0xf00000, v142
	v_lshlrev_b32_e32 v79, 12, v79
	v_lshlrev_b32_e32 v81, 16, v81
	v_or3_b32 v68, v68, v71, v69
	v_and_b32_e32 v79, 0xf000000, v79
	v_and_b32_e32 v81, 0xf0000000, v81
	v_or3_b32 v68, v68, v74, v142
	v_or3_b32 v74, v68, v79, v81
	v_mov_b32_e32 v69, s37
	v_or_b32_e32 v68, s36, v76
	v_lshl_add_u64 v[70:71], v[68:69], 1, s[90:91]
	global_store_dwordx4 v[70:71], v[64:67], off nt
	v_add_u32_e32 v70, 0x800, v47
	v_add_u32_e32 v71, 0x800, v45
	v_lshrrev_b64 v[64:65], 1, v[68:69]
	v_lshl_add_u64 v[64:65], s[78:79], 0, v[64:65]
	v_add_u32_e32 v68, 0x800, v44
	v_add_u32_e32 v69, 0x800, v46
	global_store_dword v[64:65], v74, off nt
	v_add_u32_e32 v74, 0x800, v40
	v_lshrrev_b32_e32 v65, 16, v69
	v_lshrrev_b32_e32 v64, 16, v68
	v_add_u32_e32 v79, 0x800, v42
	v_add_u32_e32 v142, 0x800, v41
	v_lshrrev_b32_e32 v66, 16, v74
	v_and_or_b32 v64, v71, s3, v64
	v_and_or_b32 v65, v70, s3, v65
	v_lshrrev_b32_e32 v68, 12, v68
	v_lshrrev_b32_e32 v71, 8, v71
	v_lshrrev_b32_e32 v69, 4, v69
	v_and_b32_e32 v70, 0xf000, v70
	v_add_u32_e32 v81, 0x800, v43
	v_lshrrev_b32_e32 v67, 16, v79
	v_and_or_b32 v66, v142, s3, v66
	v_and_b32_e32 v71, 0xf0, v71
	v_and_b32_e32 v69, 0xf00, v69
	v_lshlrev_b32_e32 v74, 4, v74
	v_lshlrev_b32_e32 v142, 8, v142
	v_and_or_b32 v68, v68, 15, v70
	v_and_or_b32 v67, v81, s3, v67
	v_and_b32_e32 v74, 0xf0000, v74
	v_and_b32_e32 v142, 0xf00000, v142
	v_lshlrev_b32_e32 v79, 12, v79
	v_lshlrev_b32_e32 v81, 16, v81
	v_or3_b32 v68, v68, v71, v69
	v_and_b32_e32 v79, 0xf000000, v79
	v_and_b32_e32 v81, 0xf0000000, v81
	v_or3_b32 v68, v68, v74, v142
	v_or3_b32 v74, v68, v79, v81
	v_mov_b32_e32 v69, s37
	v_or_b32_e32 v68, s36, v78
	v_lshl_add_u64 v[70:71], v[68:69], 1, s[90:91]
	global_store_dwordx4 v[70:71], v[64:67], off nt
	v_add_u32_e32 v70, 0x800, v39
	v_add_u32_e32 v71, 0x800, v37
	v_lshrrev_b64 v[64:65], 1, v[68:69]
	v_lshl_add_u64 v[64:65], s[78:79], 0, v[64:65]
	v_add_u32_e32 v68, 0x800, v36
	v_add_u32_e32 v69, 0x800, v38
	global_store_dword v[64:65], v74, off nt
	v_add_u32_e32 v74, 0x800, v32
	v_lshrrev_b32_e32 v65, 16, v69
	v_lshrrev_b32_e32 v64, 16, v68
	v_add_u32_e32 v79, 0x800, v34
	v_add_u32_e32 v142, 0x800, v33
	v_lshrrev_b32_e32 v66, 16, v74
	v_and_or_b32 v64, v71, s3, v64
	v_and_or_b32 v65, v70, s3, v65
	v_lshrrev_b32_e32 v68, 12, v68
	v_lshrrev_b32_e32 v71, 8, v71
	v_lshrrev_b32_e32 v69, 4, v69
	v_and_b32_e32 v70, 0xf000, v70
	v_add_u32_e32 v81, 0x800, v35
	v_lshrrev_b32_e32 v67, 16, v79
	v_and_or_b32 v66, v142, s3, v66
	v_and_b32_e32 v71, 0xf0, v71
	v_and_b32_e32 v69, 0xf00, v69
	v_lshlrev_b32_e32 v74, 4, v74
	v_lshlrev_b32_e32 v142, 8, v142
	v_and_or_b32 v68, v68, 15, v70
	v_and_or_b32 v67, v81, s3, v67
	v_and_b32_e32 v74, 0xf0000, v74
	v_and_b32_e32 v142, 0xf00000, v142
	v_lshlrev_b32_e32 v79, 12, v79
	v_lshlrev_b32_e32 v81, 16, v81
	v_or3_b32 v68, v68, v71, v69
	v_and_b32_e32 v79, 0xf000000, v79
	v_and_b32_e32 v81, 0xf0000000, v81
	v_or3_b32 v68, v68, v74, v142
	v_or3_b32 v74, v68, v79, v81
	v_mov_b32_e32 v69, s37
	v_or_b32_e32 v68, s36, v80
	v_lshl_add_u64 v[70:71], v[68:69], 1, s[90:91]
	global_store_dwordx4 v[70:71], v[64:67], off nt
	s_nop 1
	v_lshrrev_b64 v[64:65], 1, v[68:69]
	v_lshl_add_u64 v[64:65], s[78:79], 0, v[64:65]
	global_store_dword v[64:65], v74, off nt
